# P4 GLA unit loop: one static s_setprio 1 for waves 0-3 (reset at phase exit)
# speedup vs baseline: 1.0043x; 1.0043x over previous
; #define LAS __attribute__((address_space(3)))
; #define GLA_HEAD_CONSTS(hh) float wu_[16]; { const int col_ = (hh) * 128 + (tid & 127); _Pragma("unroll") for (int j = 0; j < 16; ++j) wu_[j] = a.in[I_WUP][j * 512 + col_]; } const float bd_ = a.in[I_BDEC][(hh) * 128 + (tid & 127)]
; #define PH(k) if (a.ph_lo <= (k) && (k) < a.ph_hi) { if ((k) > a.ph_lo && (k) != 6) SEAM(k);
; template <int MODE, bool dry = false>
; __device__ __forceinline__ void gla_unit(const Args& a, LAS unsigned char* lds, int idx, int h, int tid, const float (&wu)[16], float bd) {
;     constexpr int C = (MODE == 2) ? 32 : 64, TPT = C / 4, NTL = C / 16, KS_T = C / 32;
;     const int lane = tid & 63, wave = __builtin_amdgcn_readfirstlane(tid >> 6), fr = lane & 15, kq = lane >> 4;
;     LAS bf16_t* qe = (LAS bf16_t*)(lds + G_QE); LAS bf16_t* ke = (LAS bf16_t*)(lds + G_KE); LAS bf16_t* klT = (LAS bf16_t*)(lds + G_KLT);
;     LAS bf16_t* vT = (LAS bf16_t*)(lds + G_VT); LAS bf16_t* att = (LAS bf16_t*)(lds + G_ATT);
;     LAS float* psum = (LAS float*)(lds + G_PSUM); LAS float* blast = (LAS float*)(lds + G_BLAST); LAS float* dvec = (LAS float*)(lds + G_DVEC); LAS float* red = (LAS float*)(lds + G_RED);
;     const int row0 = (MODE == 2) ? MP + idx * 32 : idx * 64;
;     const bf16_t* QB = (const bf16_t*)(a.ws + A_QB); const bf16_t* KB = (const bf16_t*)(a.ws + A_KB); bf16_t* VB = (bf16_t*)(a.ws + A_VB); const bf16_t* RB = (const bf16_t*)(a.ws + A_RB);
;     const float* DLR = (const float*)((const unsigned char*)a.out + Y_DLR);
;     bf16_t* US = (bf16_t*)((unsigned char*)a.out + Y_US) + (size_t)(idx * 4 + h) * 32768;
;     bf16x8 vraw[C / 16];
; __global__ void __launch_bounds__(512) fwd_kernel(Args a) {
;     ...
;     PH(4) { GLA_HEAD_CONSTS(bx & 3);
;         for (int u = bx; u < 1024; u += G) {
;             if ((G & 3) != 0) { const int col_ = (u & 3) * 128 + (tid & 127); for (int j = 0; j < 16; ++j) wu_[j] = a.in[I_WUP][j * 512 + col_]; }
;             const float bdu = (G & 3) ? a.in[I_BDEC][(u & 3) * 128 + (tid & 127)] : bd_;
;             gla_unit<1>(a, lds, u >> 2, u & 3, tid, wu_, bdu); }
.LBB0_725:
	s_cmpk_gt_i32 s2, 0x3ff
	s_cbranch_scc1 .LBB0_745
	s_lshl_b32 s0, s2, 7
	s_and_b32 s0, s0, 0x180
	s_waitcnt vmcnt(0)
	v_and_b32_e32 v71, 0x7f, v178
	v_or_b32_e32 v0, s0, v71
	v_lshlrev_b32_e32 v64, 2, v0
	v_mov_b32_e32 v65, 0
	s_add_i32 s0, 0, 0x18400
	v_lshlrev_b32_e32 v3, 2, v71
	v_add_u32_e32 v78, s0, v3
	v_lshl_add_u64 v[14:15], s[16:17], 0, v[64:65]
	s_movk_i32 s0, 0x1000
	v_add_co_u32_e32 v16, vcc, s0, v14
	s_movk_i32 s0, 0x2000
	s_nop 0
	v_addc_co_u32_e32 v17, vcc, 0, v15, vcc
	v_add_co_u32_e32 v10, vcc, s0, v14
	s_movk_i32 s0, 0x3000
	s_nop 0
	v_addc_co_u32_e32 v11, vcc, 0, v15, vcc
	v_add_co_u32_e32 v18, vcc, s0, v14
	s_movk_i32 s0, 0x4000
	s_nop 0
	v_addc_co_u32_e32 v19, vcc, 0, v15, vcc
	v_add_co_u32_e32 v20, vcc, s0, v14
	s_movk_i32 s0, 0x5000
	s_nop 0
	v_addc_co_u32_e32 v21, vcc, 0, v15, vcc
	v_add_co_u32_e32 v22, vcc, s0, v14
	s_movk_i32 s0, 0x6000
	s_nop 0
	v_addc_co_u32_e32 v23, vcc, 0, v15, vcc
	v_add_co_u32_e32 v24, vcc, s0, v14
	s_movk_i32 s0, 0x7000
	s_nop 0
	v_addc_co_u32_e32 v25, vcc, 0, v15, vcc
	global_load_dword v79, v64, s[18:19]
	global_load_dword v0, v64, s[16:17]
	global_load_dword v1, v64, s[16:17] offset:2048
	global_load_dword v2, v[10:11], off offset:-4096
	global_load_dword v4, v[10:11], off
	global_load_dword v5, v[10:11], off offset:2048
	global_load_dword v6, v[20:21], off offset:-4096
	global_load_dword v8, v[20:21], off
	global_load_dword v9, v[20:21], off offset:2048
	s_nop 0
	global_load_dword v10, v[24:25], off offset:-4096
	global_load_dword v12, v[24:25], off
	global_load_dword v13, v[24:25], off offset:2048
	v_add_co_u32_e32 v20, vcc, s0, v14
	s_and_b32 s0, s58, 3
	s_cmp_lg_u32 s0, 0
	s_cselect_b64 s[24:25], -1, 0
	s_add_u32 s26, s54, 0x5600000
	s_addc_u32 s27, s55, 0
	s_add_u32 s28, s54, 0x7800000
	s_addc_u32 s29, s55, 0
	s_add_u32 s30, s54, 0x6700000
	s_addc_u32 s31, s55, 0
	v_lshlrev_b32_e32 v24, 4, v178
	s_add_i32 s3, 0, 0x19800
	v_and_b32_e32 v80, 15, v178
	v_lshrrev_b32_e32 v7, 1, v178
	v_add_u32_e32 v81, s3, v24
	s_add_i32 s3, 0, 0x18e00
	v_and_b32_e32 v14, 0x1e0, v7
	v_lshrrev_b32_e32 v11, 4, v176
	v_and_b32_e32 v64, 48, v176
	v_add_u32_e32 v82, s3, v3
	v_or_b32_e32 v7, 31, v7
	s_add_i32 s3, 0, 0x16000
	v_mul_u32_u24_e32 v88, 0x110, v80
	v_addc_co_u32_e32 v21, vcc, 0, v15, vcc
	v_lshl_add_u32 v3, v176, 1, 0
	v_mul_u32_u24_e32 v15, 0x90, v14
	v_mul_u32_u24_e32 v7, 0x90, v7
	v_lshlrev_b32_e32 v84, 2, v11
	v_lshl_add_u32 v95, v11, 3, s3
	v_add3_u32 v11, v88, v64, 0
	v_lshl_add_u64 v[66:67], s[52:53], 0, v[64:65]
	v_add_u32_e32 v83, 0, v64
	v_add_u32_e32 v96, 0x4400, v11
	v_lshlrev_b32_e32 v64, 1, v14
	v_add_u32_e32 v97, v3, v15
	v_add_u32_e32 v98, v3, v7
	global_load_dword v3, v[16:17], off offset:2048
	global_load_dword v7, v[18:19], off offset:2048
	global_load_dword v11, v[22:23], off offset:2048
	global_load_dword v14, v[20:21], off
	global_load_dword v15, v[20:21], off offset:2048
	v_mov_b32_e32 v25, v65
	v_lshl_add_u64 v[26:27], s[52:53], 0, v[24:25]
	s_mov_b64 s[4:5], 0x4000000
	v_lshl_add_u64 v[68:69], v[26:27], 0, s[4:5]
	v_mbcnt_lo_u32_b32 v26, -1, 0
	v_mbcnt_hi_u32_b32 v26, -1, v26
	v_and_b32_e32 v28, 64, v26
	v_xor_b32_e32 v27, 16, v26
	v_add_u32_e32 v28, 64, v28
	v_cmp_lt_i32_e32 vcc, v27, v28
	v_and_b32_e32 v24, 48, v178
	s_add_i32 s6, 0, 0x19000
	v_cndmask_b32_e32 v27, v26, v27, vcc
	v_lshlrev_b32_e32 v89, 2, v27
	v_xor_b32_e32 v27, 32, v26
	v_cmp_lt_i32_e32 vcc, v27, v28
	s_movk_i32 s0, 0x100
	v_add_u32_e32 v70, 0, v24
	v_add_u32_e32 v24, s3, v24
	v_mul_u32_u24_e32 v25, 0x90, v80
	v_or_b32_e32 v85, 16, v80
	v_or_b32_e32 v86, 32, v80
	v_or_b32_e32 v87, 48, v80
	v_cndmask_b32_e32 v26, v26, v27, vcc
	s_add_u32 s34, s54, 0x9a00000
	s_mov_b32 s21, 0
	v_cmp_gt_u32_e64 s[0:1], s0, v178
	s_movk_i32 s41, 0x90
	s_movk_i32 s43, 0x110
	v_lshlrev_b32_e32 v90, 2, v26
	v_cmp_gt_u32_e64 s[4:5], 16, v176
	v_lshl_add_u32 v91, v80, 2, s6
	s_addc_u32 s35, s55, 0
	v_lshl_add_u32 v92, v85, 2, s6
	v_lshl_add_u32 v93, v86, 2, s6
	v_lshl_add_u32 v94, v87, 2, s6
	s_mov_b32 s60, 0xbfb8aa3b
	s_mov_b32 s61, 0x800000
	s_mov_b32 s62, 0x3f317217
	s_mov_b32 s63, 0x7f800000
	s_mov_b32 s64, 0x3d800000
	v_add_u32_e32 v99, v24, v25
	s_mov_b32 s40, 0x3b800000
	s_mov_b32 s42, 0x358637bd
	v_mov_b32_e32 v100, 0x41b17218
	s_mov_b32 s44, s2
	s_cmp_lt_u32 s93, 4
	s_cbranch_scc0 .Lp4prio_done
	s_setprio 1
.Lp4prio_done:
	s_branch .LBB0_728
; __device__ __forceinline__ u32x2 pk4(f32x4 v) { u32x2 w; w.x = cvt_pk_bf16(v[0], v[1]); w.y = cvt_pk_bf16(v[2], v[3]); return w; }
; __device__ __forceinline__ f32x4 up4(u32x2 w) { return (f32x4){bf_lo(w.x), bf_hi(w.x), bf_lo(w.y), bf_hi(w.y)}; }
; template <int MODE, bool dry = false>
; __device__ __forceinline__ void gla_unit(const Args& a, LAS unsigned char* lds, int idx, int h, int tid, const float (&wu)[16], float bd) {
;     ...
;         for (int nt = 0; nt < NTL; ++nt) { const int t = 16 * nt + fr; float tot = 0.f;
; #pragma unroll
;             for (int w = 0; w < 8; ++w) tot += red[w * 64 + t];
;             const float rstd = rsqrtf(tot * (1.f / 256.f) + EPS);
; #pragma unroll
;             for (int m = 0; m < 2; ++m) { const int dv = 32 * wave + 16 * m + 4 * kq; const size_t gi = (size_t)(row0 + t) * 1024 + h * 256 + dv;
;                 const f32x4 gn = *(const f32x4*)(a.in[I_GNORM] + dv); const f32x4 rb = up4(*(const u32x2*)(RB + gi));
;                 if (!dry) *(u32x2*)(VB + gi) = pk4(o[m][nt] * rstd * gn * rb); } }
; __global__ void __launch_bounds__(512) fwd_kernel(Args a) {
;     ...
;         for (int u = bx; u < 1024; u += G) {
.LBB0_727:
	s_or_b64 exec, exec, s[6:7]
	v_or_b32_e32 v48, s46, v80
	v_ashrrev_i32_e32 v49, 31, v48
	s_lshl_b32 s6, s66, 8
	v_lshlrev_b64 v[60:61], 10, v[48:49]
	v_or_b32_e32 v52, s20, v84
	v_mov_b32_e32 v53, v65
	v_or_b32_e32 v60, s6, v60
	s_waitcnt lgkmcnt(0)
	v_lshl_add_u64 v[50:51], v[60:61], 0, v[52:53]
	v_lshlrev_b64 v[62:63], 1, v[50:51]
	v_lshl_add_u64 v[48:49], v[52:53], 2, s[22:23]
	v_lshl_add_u64 v[50:51], s[34:35], 0, v[62:63]
	s_barrier
	global_load_dwordx4 v[56:59], v[48:49], off
	global_load_dwordx2 v[72:73], v[50:51], off
	ds_read2st64_b32 v[74:75], v91 offset1:1
	ds_read2st64_b32 v[76:77], v91 offset0:2 offset1:3
	ds_read2st64_b32 v[102:103], v91 offset0:4 offset1:5
	ds_read2st64_b32 v[104:105], v91 offset0:6 offset1:7
	ds_read2st64_b32 v[106:107], v92 offset1:1
	ds_read2st64_b32 v[108:109], v92 offset0:2 offset1:3
	ds_read2st64_b32 v[110:111], v92 offset0:4 offset1:5
	ds_read2st64_b32 v[112:113], v92 offset0:6 offset1:7
	s_waitcnt lgkmcnt(7)
	v_mov_b32_e32 v115, v74
	s_waitcnt lgkmcnt(3)
	v_mov_b32_e32 v114, v106
	v_mov_b32_e32 v74, v107
	s_waitcnt lgkmcnt(2)
	v_mov_b32_e32 v106, v108
	v_mov_b32_e32 v107, v76
	v_mov_b32_e32 v76, v109
	s_waitcnt lgkmcnt(1)
	v_mov_b32_e32 v108, v110
	v_mov_b32_e32 v109, v102
	v_mov_b32_e32 v102, v111
	s_waitcnt lgkmcnt(0)
	v_mov_b32_e32 v110, v112
	v_mov_b32_e32 v111, v104
	v_mov_b32_e32 v104, v113
	v_pk_add_f32 v[112:113], v[114:115], 0 op_sel_hi:[1,0]
	v_mov_b64_e32 v[54:55], s[42:43]
	v_pk_add_f32 v[74:75], v[112:113], v[74:75]
	v_mov_b32_e32 v51, v65
	v_pk_add_f32 v[74:75], v[74:75], v[106:107]
	v_or_b32_e32 v50, 16, v52
	v_pk_add_f32 v[74:75], v[74:75], v[76:77]
	v_lshl_add_u64 v[60:61], v[60:61], 0, v[50:51]
	v_pk_add_f32 v[74:75], v[74:75], v[108:109]
	v_lshlrev_b64 v[60:61], 1, v[60:61]
	v_pk_add_f32 v[74:75], v[74:75], v[102:103]
	v_lshl_add_u64 v[62:63], s[28:29], 0, v[62:63]
	v_pk_add_f32 v[74:75], v[74:75], v[110:111]
	s_add_i32 s44, s44, s58
	v_pk_add_f32 v[74:75], v[74:75], v[104:105]
	s_cmpk_lt_i32 s44, 0x400
	v_pk_fma_f32 v[74:75], v[74:75], s[40:41], v[54:55] op_sel_hi:[1,0,0]
	s_nop 0
	v_mul_f32_e32 v76, 0x4b800000, v75
	v_cmp_gt_f32_e32 vcc, s61, v75
	s_nop 1
	v_cndmask_b32_e32 v75, v75, v76, vcc
	v_rsq_f32_e32 v75, v75
	v_lshl_add_u64 v[76:77], s[34:35], 0, v[60:61]
	v_lshl_add_u64 v[60:61], s[28:29], 0, v[60:61]
	v_mul_f32_e32 v101, 0x45800000, v75
	v_cndmask_b32_e32 v102, v75, v101, vcc
	v_pk_mul_f32 v[46:47], v[46:47], v[102:103] op_sel_hi:[1,0]
	v_pk_mul_f32 v[44:45], v[44:45], v[102:103] op_sel_hi:[1,0]
	v_pk_mul_f32 v[42:43], v[42:43], v[102:103] op_sel_hi:[1,0]
	v_pk_mul_f32 v[40:41], v[40:41], v[102:103] op_sel_hi:[1,0]
	v_cmp_gt_f32_e32 vcc, s61, v74
	s_waitcnt vmcnt(1)
	v_pk_mul_f32 v[44:45], v[56:57], v[44:45]
	v_pk_mul_f32 v[46:47], v[58:59], v[46:47]
	s_waitcnt vmcnt(0)
	v_lshlrev_b32_e32 v56, 16, v72
	v_and_b32_e32 v57, 0xffff0000, v72
	v_lshlrev_b32_e32 v58, 16, v73
	v_and_b32_e32 v59, 0xffff0000, v73
	v_pk_mul_f32 v[46:47], v[46:47], v[58:59]
	v_pk_mul_f32 v[44:45], v[44:45], v[56:57]
	v_or_b32_e32 v58, s46, v85
	v_cvt_pk_bf16_f32 v44, v44, v45
	v_cvt_pk_bf16_f32 v45, v46, v47
	global_store_dwordx2 v[62:63], v[44:45], off
	global_load_dwordx2 v[56:57], v[76:77], off
	s_nop 0
	global_load_dwordx4 v[44:47], v[48:49], off offset:64
	v_ashrrev_i32_e32 v59, 31, v58
	v_lshlrev_b64 v[58:59], 10, v[58:59]
	v_or_b32_e32 v58, s6, v58
	v_lshl_add_u64 v[62:63], v[58:59], 0, v[52:53]
	v_lshlrev_b64 v[62:63], 1, v[62:63]
	v_lshl_add_u64 v[72:73], s[34:35], 0, v[62:63]
	s_waitcnt vmcnt(1)
	v_lshlrev_b32_e32 v76, 16, v56
	v_and_b32_e32 v77, 0xffff0000, v56
	v_lshlrev_b32_e32 v56, 16, v57
	v_and_b32_e32 v57, 0xffff0000, v57
	s_waitcnt vmcnt(0)
	v_pk_mul_f32 v[40:41], v[44:45], v[40:41]
	v_pk_mul_f32 v[42:43], v[46:47], v[42:43]
	v_pk_mul_f32 v[40:41], v[40:41], v[76:77]
	v_pk_mul_f32 v[42:43], v[42:43], v[56:57]
	v_cvt_pk_bf16_f32 v40, v40, v41
	v_cvt_pk_bf16_f32 v41, v42, v43
	global_store_dwordx2 v[60:61], v[40:41], off
	global_load_dwordx2 v[44:45], v[72:73], off
	s_nop 0
	global_load_dwordx4 v[40:43], v[48:49], off
	v_mul_f32_e32 v56, 0x4b800000, v74
	v_cndmask_b32_e32 v56, v74, v56, vcc
	v_rsq_f32_e32 v60, v56
	v_lshl_add_u64 v[56:57], s[28:29], 0, v[62:63]
	v_lshl_add_u64 v[46:47], v[58:59], 0, v[50:51]
	v_lshlrev_b64 v[46:47], 1, v[46:47]
	v_mul_f32_e32 v61, 0x45800000, v60
	v_cndmask_b32_e32 v60, v60, v61, vcc
	v_pk_mul_f32 v[38:39], v[38:39], v[60:61] op_sel_hi:[1,0]
	v_pk_mul_f32 v[36:37], v[36:37], v[60:61] op_sel_hi:[1,0]
	v_lshl_add_u64 v[58:59], s[34:35], 0, v[46:47]
	v_pk_mul_f32 v[34:35], v[34:35], v[60:61] op_sel_hi:[1,0]
	v_pk_mul_f32 v[32:33], v[32:33], v[60:61] op_sel_hi:[1,0]
	v_lshl_add_u64 v[46:47], s[28:29], 0, v[46:47]
	s_waitcnt vmcnt(1)
	v_lshlrev_b32_e32 v62, 16, v44
	v_and_b32_e32 v63, 0xffff0000, v44
	v_lshlrev_b32_e32 v44, 16, v45
	v_and_b32_e32 v45, 0xffff0000, v45
	s_waitcnt vmcnt(0)
	v_pk_mul_f32 v[36:37], v[40:41], v[36:37]
	v_pk_mul_f32 v[38:39], v[42:43], v[38:39]
	v_pk_mul_f32 v[36:37], v[36:37], v[62:63]
	v_pk_mul_f32 v[38:39], v[38:39], v[44:45]
	v_cvt_pk_bf16_f32 v36, v36, v37
	v_cvt_pk_bf16_f32 v37, v38, v39
	global_store_dwordx2 v[56:57], v[36:37], off
	global_load_dwordx2 v[40:41], v[58:59], off
	s_nop 0
	global_load_dwordx4 v[36:39], v[48:49], off offset:64
	v_or_b32_e32 v42, s46, v86
	v_ashrrev_i32_e32 v43, 31, v42
	v_lshlrev_b64 v[42:43], 10, v[42:43]
	v_or_b32_e32 v42, s6, v42
	v_lshl_add_u64 v[44:45], v[42:43], 0, v[52:53]
	v_lshlrev_b64 v[44:45], 1, v[44:45]
	v_lshl_add_u64 v[56:57], s[34:35], 0, v[44:45]
	v_lshl_add_u64 v[42:43], v[42:43], 0, v[50:51]
	s_waitcnt vmcnt(1)
; __device__ __forceinline__ u32x2 pk4(f32x4 v) { u32x2 w; w.x = cvt_pk_bf16(v[0], v[1]); w.y = cvt_pk_bf16(v[2], v[3]); return w; }
; __device__ __forceinline__ f32x4 up4(u32x2 w) { return (f32x4){bf_lo(w.x), bf_hi(w.x), bf_lo(w.y), bf_hi(w.y)}; }
; template <int MODE, bool dry = false>
; __device__ __forceinline__ void gla_unit(const Args& a, LAS unsigned char* lds, int idx, int h, int tid, const float (&wu)[16], float bd) {
;     ...
;         for (int nt = 0; nt < NTL; ++nt) { const int t = 16 * nt + fr; float tot = 0.f;
; #pragma unroll
;             for (int w = 0; w < 8; ++w) tot += red[w * 64 + t];
;             const float rstd = rsqrtf(tot * (1.f / 256.f) + EPS);
; #pragma unroll
;             for (int m = 0; m < 2; ++m) { const int dv = 32 * wave + 16 * m + 4 * kq; const size_t gi = (size_t)(row0 + t) * 1024 + h * 256 + dv;
;                 const f32x4 gn = *(const f32x4*)(a.in[I_GNORM] + dv); const f32x4 rb = up4(*(const u32x2*)(RB + gi));
;                 if (!dry) *(u32x2*)(VB + gi) = pk4(o[m][nt] * rstd * gn * rb); } }
;     }
;     __syncthreads();
	v_lshlrev_b32_e32 v58, 16, v40
	v_and_b32_e32 v59, 0xffff0000, v40
	v_lshlrev_b32_e32 v40, 16, v41
	v_and_b32_e32 v41, 0xffff0000, v41
	s_waitcnt vmcnt(0)
	v_pk_mul_f32 v[32:33], v[36:37], v[32:33]
	v_pk_mul_f32 v[34:35], v[38:39], v[34:35]
	v_pk_mul_f32 v[32:33], v[32:33], v[58:59]
	v_pk_mul_f32 v[34:35], v[34:35], v[40:41]
	v_cvt_pk_bf16_f32 v32, v32, v33
	v_cvt_pk_bf16_f32 v33, v34, v35
	global_store_dwordx2 v[46:47], v[32:33], off
	global_load_dwordx2 v[36:37], v[56:57], off
	s_nop 0
	global_load_dwordx4 v[32:35], v[48:49], off
	ds_read2st64_b32 v[38:39], v93 offset1:1
	ds_read2st64_b32 v[40:41], v93 offset0:2 offset1:3
	ds_read2st64_b32 v[46:47], v93 offset0:4 offset1:5
	ds_read2st64_b32 v[56:57], v93 offset0:6 offset1:7
	ds_read2st64_b32 v[58:59], v94 offset1:1
	ds_read2st64_b32 v[60:61], v94 offset0:2 offset1:3
	ds_read2st64_b32 v[62:63], v94 offset0:4 offset1:5
	ds_read2st64_b32 v[72:73], v94 offset0:6 offset1:7
	s_waitcnt lgkmcnt(7)
	v_mov_b32_e32 v75, v38
	s_waitcnt lgkmcnt(3)
	v_mov_b32_e32 v74, v58
	v_mov_b32_e32 v38, v59
	s_waitcnt lgkmcnt(2)
	v_mov_b32_e32 v58, v60
	v_mov_b32_e32 v59, v40
	v_mov_b32_e32 v40, v61
	s_waitcnt lgkmcnt(1)
	v_mov_b32_e32 v60, v62
	v_mov_b32_e32 v61, v46
	v_mov_b32_e32 v46, v63
	s_waitcnt lgkmcnt(0)
	v_mov_b32_e32 v62, v72
	v_mov_b32_e32 v63, v56
	v_mov_b32_e32 v56, v73
	v_pk_add_f32 v[72:73], v[74:75], 0 op_sel_hi:[1,0]
	s_nop 0
	v_pk_add_f32 v[38:39], v[72:73], v[38:39]
	s_nop 0
	v_pk_add_f32 v[38:39], v[38:39], v[58:59]
	s_nop 0
	v_pk_add_f32 v[38:39], v[38:39], v[40:41]
	s_nop 0
	v_pk_add_f32 v[38:39], v[38:39], v[60:61]
	s_nop 0
	v_pk_add_f32 v[38:39], v[38:39], v[46:47]
	s_nop 0
	v_pk_add_f32 v[38:39], v[38:39], v[62:63]
	s_nop 0
	v_pk_add_f32 v[38:39], v[38:39], v[56:57]
	s_nop 0
	v_pk_fma_f32 v[38:39], v[38:39], s[40:41], v[54:55] op_sel_hi:[1,0,0]
	s_waitcnt vmcnt(1)
	v_lshlrev_b32_e32 v54, 16, v36
	v_mul_f32_e32 v40, 0x4b800000, v39
	v_cmp_gt_f32_e32 vcc, s61, v39
	v_and_b32_e32 v55, 0xffff0000, v36
	v_lshlrev_b32_e32 v36, 16, v37
	v_cndmask_b32_e32 v39, v39, v40, vcc
	v_rsq_f32_e32 v39, v39
	v_and_b32_e32 v37, 0xffff0000, v37
	v_lshlrev_b64 v[40:41], 1, v[42:43]
	v_lshl_add_u64 v[42:43], s[28:29], 0, v[44:45]
	v_mul_f32_e32 v46, 0x45800000, v39
	v_cndmask_b32_e32 v46, v39, v46, vcc
	v_pk_mul_f32 v[30:31], v[30:31], v[46:47] op_sel_hi:[1,0]
	v_pk_mul_f32 v[28:29], v[28:29], v[46:47] op_sel_hi:[1,0]
	s_waitcnt vmcnt(0)
	v_pk_mul_f32 v[30:31], v[34:35], v[30:31]
	v_pk_mul_f32 v[28:29], v[32:33], v[28:29]
	v_pk_mul_f32 v[30:31], v[30:31], v[36:37]
	v_pk_mul_f32 v[28:29], v[28:29], v[54:55]
	v_lshl_add_u64 v[44:45], s[34:35], 0, v[40:41]
	v_cvt_pk_bf16_f32 v28, v28, v29
	v_cvt_pk_bf16_f32 v29, v30, v31
	global_store_dwordx2 v[42:43], v[28:29], off
	global_load_dwordx2 v[32:33], v[44:45], off
	s_nop 0
	global_load_dwordx4 v[28:31], v[48:49], off offset:64
	v_or_b32_e32 v34, s65, v87
	v_ashrrev_i32_e32 v35, 31, v34
	v_lshlrev_b64 v[34:35], 10, v[34:35]
	v_pk_mul_f32 v[26:27], v[26:27], v[46:47] op_sel_hi:[1,0]
	v_pk_mul_f32 v[24:25], v[24:25], v[46:47] op_sel_hi:[1,0]
	v_or_b32_e32 v34, s6, v34
	v_lshl_add_u64 v[36:37], v[34:35], 0, v[52:53]
	v_lshlrev_b64 v[36:37], 1, v[36:37]
	v_lshl_add_u64 v[40:41], s[28:29], 0, v[40:41]
	v_lshl_add_u64 v[42:43], s[34:35], 0, v[36:37]
	v_cmp_gt_f32_e32 vcc, s61, v38
	s_waitcnt vmcnt(1)
	v_lshlrev_b32_e32 v44, 16, v32
	v_and_b32_e32 v45, 0xffff0000, v32
	v_lshlrev_b32_e32 v32, 16, v33
	v_and_b32_e32 v33, 0xffff0000, v33
	s_waitcnt vmcnt(0)
	v_pk_mul_f32 v[24:25], v[28:29], v[24:25]
	v_pk_mul_f32 v[26:27], v[30:31], v[26:27]
	v_pk_mul_f32 v[24:25], v[24:25], v[44:45]
	v_pk_mul_f32 v[26:27], v[26:27], v[32:33]
	v_cvt_pk_bf16_f32 v24, v24, v25
	v_cvt_pk_bf16_f32 v25, v26, v27
	global_store_dwordx2 v[40:41], v[24:25], off
	global_load_dwordx2 v[28:29], v[42:43], off
	s_nop 0
	global_load_dwordx4 v[24:27], v[48:49], off
	v_mul_f32_e32 v32, 0x4b800000, v38
	v_cndmask_b32_e32 v32, v38, v32, vcc
	v_rsq_f32_e32 v38, v32
	v_lshl_add_u64 v[32:33], s[28:29], 0, v[36:37]
	v_lshl_add_u64 v[30:31], v[34:35], 0, v[50:51]
	v_lshlrev_b64 v[30:31], 1, v[30:31]
	v_mul_f32_e32 v36, 0x45800000, v38
	v_cndmask_b32_e32 v36, v38, v36, vcc
	v_pk_mul_f32 v[22:23], v[22:23], v[36:37] op_sel_hi:[1,0]
	v_pk_mul_f32 v[20:21], v[20:21], v[36:37] op_sel_hi:[1,0]
	v_lshl_add_u64 v[34:35], s[34:35], 0, v[30:31]
	v_pk_mul_f32 v[18:19], v[18:19], v[36:37] op_sel_hi:[1,0]
	v_pk_mul_f32 v[16:17], v[16:17], v[36:37] op_sel_hi:[1,0]
	s_waitcnt vmcnt(1)
	v_lshlrev_b32_e32 v38, 16, v28
	v_and_b32_e32 v39, 0xffff0000, v28
	v_lshlrev_b32_e32 v28, 16, v29
	v_and_b32_e32 v29, 0xffff0000, v29
	s_waitcnt vmcnt(0)
	v_pk_mul_f32 v[20:21], v[24:25], v[20:21]
	v_pk_mul_f32 v[22:23], v[26:27], v[22:23]
	v_pk_mul_f32 v[20:21], v[20:21], v[38:39]
	v_pk_mul_f32 v[22:23], v[22:23], v[28:29]
	v_cvt_pk_bf16_f32 v20, v20, v21
	v_cvt_pk_bf16_f32 v21, v22, v23
	global_store_dwordx2 v[32:33], v[20:21], off
	global_load_dwordx2 v[24:25], v[34:35], off
	s_nop 0
	global_load_dwordx4 v[20:23], v[48:49], off offset:64
	v_lshl_add_u64 v[26:27], s[28:29], 0, v[30:31]
	s_waitcnt vmcnt(1)
	v_lshlrev_b32_e32 v28, 16, v24
	v_and_b32_e32 v29, 0xffff0000, v24
	v_lshlrev_b32_e32 v24, 16, v25
	v_and_b32_e32 v25, 0xffff0000, v25
	s_waitcnt vmcnt(0)
	v_pk_mul_f32 v[16:17], v[20:21], v[16:17]
	v_pk_mul_f32 v[18:19], v[22:23], v[18:19]
	v_pk_mul_f32 v[16:17], v[16:17], v[28:29]
	v_pk_mul_f32 v[18:19], v[18:19], v[24:25]
	v_cvt_pk_bf16_f32 v16, v16, v17
	v_cvt_pk_bf16_f32 v17, v18, v19
	global_store_dwordx2 v[26:27], v[16:17], off
	s_barrier
	s_cbranch_scc0 .LBB0_745

; __device__ __forceinline__ unsigned xb_add(unsigned* p, unsigned v) { return __hip_atomic_fetch_add(p, v, __ATOMIC_RELAXED, __HIP_MEMORY_SCOPE_AGENT); }
; __device__ __forceinline__ void xcd_barrier(const XcdBarrier& b) {
;     asm volatile("s_waitcnt vmcnt(0)" ::: "memory");
;     __syncthreads();
;     if (threadIdx.x == 0) {
;         unsigned* bar = b.bar;
;         __builtin_amdgcn_s_waitcnt(0);
;         unsigned nloc = b.st[0], nx = b.st[1];
;         if (nloc == 0u) { xcd_barrier_complete(bar, b.x, nloc, nx); b.st[0] = nloc; b.st[1] = nx; }
;         const unsigned old = xb_add(&bar[XB_XSUB(b.x)], 1u);
;         const unsigned gen = old / nloc;
;         if (old + 1u == (gen + 1u) * nloc) {
;             __builtin_amdgcn_fence(__ATOMIC_RELEASE, "agent");
;             asm volatile("s_waitcnt vmcnt(0)" ::: "memory");
;             const unsigned og = xb_add(&bar[XB_TOP], 1u);
;             const unsigned tg = og / nx;
;             if (og + 1u == (tg + 1u) * nx) xb_add(&bar[XB_TOPGEN], 1u);
.LBB0_745:
	s_setprio 0
	s_cmp_lt_i32 s56, 6
	s_cselect_b64 s[0:1], -1, 0
	s_cmp_gt_i32 s57, 5
	s_cselect_b64 s[4:5], -1, 0
	s_and_b64 s[0:1], s[0:1], s[4:5]
	s_andn2_b64 vcc, exec, s[0:1]
	s_cbranch_vccnz .LBB0_841
	s_andn2_b64 vcc, exec, s[14:15]
	s_cbranch_vccnz .LBB0_800
	s_getreg_b32 s3, hwreg(HW_REG_XCC_ID, 0, 4)
	s_waitcnt vmcnt(0)
	v_cmp_eq_u32_e32 vcc, 0, v178
	s_waitcnt vmcnt(0)
	s_barrier
	s_and_saveexec_b64 s[0:1], vcc
	s_cbranch_execz .LBB0_799
	buffer_inv sc1
	v_mov_b32_e32 v0, 0x23ff0
	ds_read2_b32 v[0:1], v0 offset1:1
	s_and_b32 s98, s3, 15
	s_lshl_b32 s98, s98, 8
	s_add_u32 s98, s54, s98
	s_addc_u32 s99, s55, 0
	s_add_u32 s98, s98, 0x22a3400
	s_addc_u32 s99, s99, 0
	v_mov_b32_e32 v2, 0
	v_mov_b32_e32 v3, 1
	global_atomic_add v4, v2, v3, s[98:99] sc0
	s_add_u32 s100, s54, 0x22a5400
	s_addc_u32 s101, s55, 0
	s_waitcnt vmcnt(0) lgkmcnt(0)
	v_mul_u32_u24_e32 v0, 5, v0
	v_mul_u32_u24_e32 v1, 5, v1
	v_add_u32_e32 v4, 1, v4
	v_cmp_eq_u32_e32 vcc, v4, v0
	s_cbranch_vccz .Lxb_poll_s4
	buffer_wbl2 sc1
	s_waitcnt vmcnt(0)
	global_atomic_add v2, v3, s[100:101]
